# P0 work distribution: heavy modulation workgroups take 4 light units, others 11-12 consecutive light units
# speedup vs baseline: 1.3739x; 1.0042x over previous
.LBB0_17:
	s_or_b64 exec, exec, s[0:1]
	v_readlane_b32 s0, v255, 0
	s_cmpk_gt_i32 s0, 0x8e0
	s_cbranch_scc1 .LBB0_75
	v_mov_b32_e32 v33, 0
	s_movk_i32 s13, 0x400
	s_mov_b32 s28, 0xc2fc0000
	s_mov_b32 s5, 0
	s_movk_i32 s29, 0x1ff
	s_mov_b64 s[6:7], 0x1092000
	s_movk_i32 s30, 0x1000
	s_mov_b64 s[10:11], 0x1093000
	s_mov_b64 s[14:15], 0x800
	s_movk_i32 s31, 0x100
	s_mov_b64 s[16:17], 0x1000
	s_movk_i32 s33, 0x800
	s_movk_i32 s34, 0x3000
	s_mov_b64 s[18:19], 0x2d000
	s_mov_b64 s[20:21], 0x30000
	s_movk_i32 s35, 0x300
	s_movk_i32 s39, 0xc0
	s_movk_i32 s40, 0xc00
	s_movk_i32 s41, 0x104
	s_mov_b64 s[22:23], 0xc80000
	s_movk_i32 s42, 0x5ff
	s_movk_i32 s43, 0xc28
	s_movk_i32 s44, 0x30a0
	s_mov_b32 s45, 0x3fffff0
	v_mov_b32_e32 v42, 0x42800000
	v_not_b32_e32 v43, 63
	v_mov_b32_e32 v44, 0x100
	v_readlane_b32 s46, v255, 0
	s_nop 3
	s_mov_b32 s101, -1
	s_cmpk_lg_i32 s36, 0x100
	s_cbranch_scc1 .LBB0_20
	s_cmp_lt_u32 s46, 96
	s_cbranch_scc0 .Lp0_light
	s_lshl_b32 s100, s46, 2
	s_add_i32 s100, s100, 96
	s_mov_b32 s101, 4
	s_branch .LBB0_20
.Lp0_light:
	s_sub_i32 s100, s46, 96
	s_min_u32 s101, s100, 33
	s_mul_i32 s46, s100, 11
	s_add_i32 s46, s46, s101
	s_add_i32 s46, s46, 480
	s_cmp_lt_u32 s100, 33
	s_cselect_b32 s101, 11, 10
	s_add_i32 s100, s46, 1
	s_branch .LBB0_20
.LBB0_19:
	s_cmp_eq_u32 s101, -1
	s_cbranch_scc1 .Lp0_stride
	s_cmp_eq_u32 s101, 0
	s_cbranch_scc1 .LBB0_75
	s_mov_b32 s46, s100
	s_add_i32 s100, s100, 1
	s_sub_i32 s101, s101, 1
	s_branch .LBB0_20
